# v14
# speedup vs baseline: 1.0019x; 1.0019x over previous
.LBB0_54:
	v_exp_f32_e32 v238, v80
	v_exp_f32_e32 v240, v81
	v_exp_f32_e32 v241, v82
	v_exp_f32_e32 v243, v83
	v_exp_f32_e32 v244, v84
	v_exp_f32_e32 v133, v64
	v_exp_f32_e32 v132, v66
	v_add_f32_e32 v64, 0, v238
	v_add_f32_e32 v66, 0, v148
	v_exp_f32_e32 v245, v85
	v_add_f32_e32 v64, v240, v64
	v_add_f32_e32 v66, v149, v66
	v_exp_f32_e32 v239, v86
	v_add_f32_e32 v64, v241, v64
	v_add_f32_e32 v66, v150, v66
	v_exp_f32_e32 v242, v87
	v_add_f32_e32 v64, v243, v64
	v_add_f32_e32 v66, v151, v66
	v_exp_f32_e32 v234, v88
	v_add_f32_e32 v64, v244, v64
	v_add_f32_e32 v66, v155, v66
	v_exp_f32_e32 v235, v89
	v_add_f32_e32 v64, v245, v64
	v_add_f32_e32 v66, v168, v66
	v_exp_f32_e32 v236, v90
	v_add_f32_e32 v64, v239, v64
	v_add_f32_e32 v66, v169, v66
	v_exp_f32_e32 v237, v91
	v_add_f32_e32 v64, v242, v64
	v_add_f32_e32 v66, v170, v66
	v_exp_f32_e32 v230, v92
	v_add_f32_e32 v64, v234, v64
	v_add_f32_e32 v66, v171, v66
	v_exp_f32_e32 v232, v93
	v_add_f32_e32 v64, v235, v64
	v_add_f32_e32 v66, v191, v66
	v_exp_f32_e32 v231, v94
	v_add_f32_e32 v64, v236, v64
	v_add_f32_e32 v66, v192, v66
	v_exp_f32_e32 v233, v95
	v_add_f32_e32 v64, v237, v64
	v_add_f32_e32 v66, v195, v66
	v_add_f32_e32 v64, v230, v64
	v_add_f32_e32 v66, v196, v66
	v_exp_f32_e32 v226, v65
	v_add_f32_e32 v64, v232, v64
	v_add_f32_e32 v66, v197, v66
	v_add_f32_e32 v64, v231, v64
	v_add_f32_e32 v66, v198, v66
	v_exp_f32_e32 v134, v67
	v_add_f32_e32 v64, v233, v64
	v_add_f32_e32 v66, v199, v66
	v_exp_f32_e32 v135, v68
	v_add_f32_e32 v64, v133, v64
	v_add_f32_e32 v66, v200, v66
	v_exp_f32_e32 v227, v69
	v_add_f32_e32 v64, v226, v64
	v_add_f32_e32 v66, v201, v66
	v_mad_i64_i32 v[156:157], s[8:9], v139, s73, 0
	v_mad_i64_i32 v[158:159], s[8:9], v140, s73, 0
	v_mad_i64_i32 v[160:161], s[8:9], v141, s73, 0
	v_mad_i64_i32 v[162:163], s[8:9], v142, s73, 0
	v_mad_i64_i32 v[164:165], s[8:9], v143, s73, 0
	v_mad_i64_i32 v[166:167], s[8:9], v144, s73, 0
	v_exp_f32_e32 v228, v70
	v_add_f32_e32 v64, v132, v64
	v_add_f32_e32 v66, v211, v66
	v_exp_f32_e32 v229, v71
	v_add_f32_e32 v64, v134, v64
	v_add_f32_e32 v66, v212, v66
	v_readlane_b32 s8, v255, 9
	v_exp_f32_e32 v124, v72
	v_add_f32_e32 v64, v135, v64
	v_add_f32_e32 v66, v213, v66
	s_add_u32 s46, s8, s10
	v_readlane_b32 s8, v255, 10
	v_exp_f32_e32 v125, v73
	v_add_f32_e32 v64, v227, v64
	v_add_f32_e32 v66, v214, v66
	s_addc_u32 s47, s8, s11
	v_exp_f32_e32 v126, v74
	v_add_f32_e32 v64, v228, v64
	v_add_f32_e32 v66, v215, v66
	s_add_u32 s20, s78, s10
	v_exp_f32_e32 v127, v75
	v_add_f32_e32 v64, v229, v64
	v_add_f32_e32 v66, v216, v66
	s_addc_u32 s21, s79, s11
	v_exp_f32_e32 v128, v76
	v_add_f32_e32 v64, v124, v64
	v_add_f32_e32 v66, v217, v66
	s_cmp_lg_u32 0, -1
	v_exp_f32_e32 v129, v77
	v_add_f32_e32 v64, v125, v64
	v_add_f32_e32 v66, v218, v66
	s_cselect_b32 s8, 0, 0
	v_exp_f32_e32 v130, v78
	v_add_f32_e32 v64, v126, v64
	v_add_f32_e32 v66, v219, v66
	s_addk_i32 s8, 0x4000
	v_exp_f32_e32 v131, v79
	v_add_f32_e32 v64, v127, v64
	v_add_f32_e32 v66, v220, v66
	s_add_u32 s10, s23, s10
	v_add_f32_e32 v64, v128, v64
	v_add_f32_e32 v66, v221, v66
	s_addc_u32 s11, s22, s11
	v_add_f32_e32 v64, v129, v64
	v_add_f32_e32 v66, v222, v66
	s_add_u32 s77, s18, s10
	v_add_f32_e32 v64, v130, v64
	v_add_f32_e32 v66, v223, v66
	s_addc_u32 s66, s19, s11
	s_lshr_b32 s10, s27, 7
	v_add_f32_e32 v194, v131, v64
	v_bfe_u32 v64, v138, 4, 4
	v_bfe_u32 v65, v138, 3, 4
	v_add_f32_e32 v66, v224, v66
	s_mul_i32 s10, s10, 0xc0000
	v_add_f32_e32 v192, 0, v66
	s_mov_b32 s25, 1
	v_add_u32_e32 v195, s8, v172
	v_cmp_gt_u32_e64 s[8:9], 32, v137
	v_lshl_add_u32 v191, v136, 2, s59
	v_mul_u32_u24_e32 v168, 0x1800, v64
	v_mov_b32_e32 v169, v181
	v_mul_u32_u24_e32 v170, 0x1800, v65
	v_mov_b32_e32 v171, v181
	s_add_u32 s67, s10, 0xffe80000
	s_add_u32 s88, s10, 0xfff40000
	s_mov_b64 s[22:23], 0
	s_waitcnt lgkmcnt(0)
	s_barrier
	s_mov_b32 s100, 0x8000
	s_mov_b32 s101, 0x18800
	s_mov_b32 s89, 0x14000
	s_mov_b32 s25, 0x20800
	v_fma_f32 v192, v192, v193, v194
	v_cvt_pk_bf16_f32 v250, v238, v240
	v_cvt_pk_bf16_f32 v251, v241, v243
	v_cvt_pk_bf16_f32 v252, v244, v245
	v_cvt_pk_bf16_f32 v253, v239, v242
	v_cvt_pk_bf16_f32 v238, v234, v235
	v_cvt_pk_bf16_f32 v239, v236, v237
	v_cvt_pk_bf16_f32 v240, v230, v232
	v_cvt_pk_bf16_f32 v241, v231, v233
	v_cvt_pk_bf16_f32 v242, v133, v226
	v_cvt_pk_bf16_f32 v243, v132, v134
	v_cvt_pk_bf16_f32 v244, v135, v227
	v_cvt_pk_bf16_f32 v245, v228, v229
	v_cvt_pk_bf16_f32 v246, v124, v125
	v_cvt_pk_bf16_f32 v247, v126, v127
	v_cvt_pk_bf16_f32 v248, v128, v129
	v_cvt_pk_bf16_f32 v249, v130, v131
	s_nop 1
	v_permlane32_swap_b32_e32 v250, v252
	v_permlane32_swap_b32_e32 v251, v253
	v_permlane32_swap_b32_e32 v238, v240
	v_permlane32_swap_b32_e32 v239, v241
	v_permlane32_swap_b32_e32 v242, v244
	v_permlane32_swap_b32_e32 v243, v245
	v_permlane32_swap_b32_e32 v246, v248
	v_permlane32_swap_b32_e32 v247, v249
	v_mov_b32_e32 v234, v250
	v_mov_b32_e32 v235, v251
	v_mov_b32_e32 v236, v252
	v_mov_b32_e32 v237, v253
	v_xor_b32_e32 v196, 0x80000000, v190
	v_mov_b32_e32 v197, v196
	v_mov_b32_e32 v198, v196
	v_mov_b32_e32 v199, v196
	v_mov_b32_e32 v200, v196
	v_mov_b32_e32 v201, v196
	v_mov_b32_e32 v202, v196
	v_mov_b32_e32 v203, v196
	v_mov_b32_e32 v204, v196
	v_mov_b32_e32 v205, v196
	v_mov_b32_e32 v206, v196
	v_mov_b32_e32 v207, v196
	v_mov_b32_e32 v208, v196
	v_mov_b32_e32 v209, v196
	v_mov_b32_e32 v210, v196
	v_mov_b32_e32 v211, v196
	v_mov_b32_e32 v253, 1.0
	v_add_u32_e32 v156, v156, v180
	v_add_u32_e32 v158, v158, v180
	v_add_u32_e32 v160, v160, v154
	v_add_u32_e32 v162, v162, v154
	v_add_u32_e32 v164, v164, v180
	v_add_u32_e32 v166, v166, v180
	v_add_u32_e32 v168, v168, v180
	v_add_u32_e32 v170, v170, v154
	v_add_u32_e32 v193, s89, v182
	v_add_u32_e32 v194, s89, v186
	v_add_u32_e32 v232, s89, v187
	v_add_u32_e32 v233, s89, v188
	ds_read_b128 v[228:231], v193
	ds_read_b128 v[224:227], v193 offset:4096
	s_cmp_eq_u32 s67, s22
	s_cbranch_scc1 .Lda1_sl_laste
	s_add_u32 s10, s77, s22
	s_addc_u32 s11, s66, s23
	s_add_u32 s48, s10, 0x126c3400
	s_addc_u32 s49, s11, 0
	s_add_u32 s50, s77, s22
	s_addc_u32 s51, s66, s23
	s_add_u32 s50, s50, 0x126c2c00
	s_addc_u32 s51, s51, 0
	global_load_dwordx4 v[128:131], v156, s[48:49]
	global_load_dwordx4 v[124:127], v158, s[48:49]
	global_load_dwordx4 v[132:135], v160, s[50:51]
	global_load_dwordx4 v[112:115], v166, s[48:49]
	global_load_dwordx4 v[116:119], v164, s[48:49]
	global_load_dwordx4 v[120:123], v162, s[50:51]
	s_branch .Lda1_entry_sl

.Lda1_entry_sl:
.LBB0_55:
	s_sub_i32 s11, 0x20800, s100
	s_sub_i32 s11, s11, s101
	v_add_u32_e32 v189, s11, v195
	s_waitcnt lgkmcnt(1)
	v_mfma_f32_32x32x16_bf16 v[80:95], v[228:231], v[108:111], v[196:211]
	ds_read_b128 v[228:231], v194
	s_waitcnt lgkmcnt(1)
	v_mfma_f32_32x32x16_bf16 v[64:79], v[224:227], v[108:111], v[196:211]
	ds_read_b128 v[224:227], v194 offset:4096
	s_waitcnt lgkmcnt(1)
	v_mfma_f32_32x32x16_bf16 v[80:95], v[228:231], v[104:107], v[80:95]
	ds_read_b128 v[228:231], v232
	s_waitcnt lgkmcnt(1)
	v_mfma_f32_32x32x16_bf16 v[64:79], v[224:227], v[104:107], v[64:79]
	ds_read_b128 v[224:227], v232 offset:4096
	s_waitcnt lgkmcnt(1)
	v_mfma_f32_32x32x16_bf16 v[80:95], v[228:231], v[100:103], v[80:95]
	ds_read_b128 v[228:231], v233
	s_waitcnt lgkmcnt(1)
	v_mfma_f32_32x32x16_bf16 v[64:79], v[224:227], v[100:103], v[64:79]
	ds_read_b128 v[224:227], v233 offset:4096
	ds_read_b64_tr_b16 v[212:213], v189 offset:0
	ds_read_b64_tr_b16 v[214:215], v189 offset:0x800
	ds_read_b64_tr_b16 v[216:217], v189 offset:0x1000
	ds_read_b64_tr_b16 v[218:219], v189 offset:0x1800
	ds_read_b64_tr_b16 v[220:221], v189 offset:0x2000
	ds_read_b64_tr_b16 v[222:223], v189 offset:0x2800
	s_waitcnt lgkmcnt(7)
	v_mfma_f32_32x32x16_bf16 v[80:95], v[228:231], v[96:99], v[80:95]
	s_waitcnt lgkmcnt(6)
	v_mfma_f32_32x32x16_bf16 v[64:79], v[224:227], v[96:99], v[64:79]
	ds_read_b64_tr_b16 v[224:225], v189 offset:0x3000
	ds_read_b64_tr_b16 v[226:227], v189 offset:0x3800
	s_waitcnt lgkmcnt(4)
	v_mfma_f32_32x32x16_bf16 v[0:15], v[234:237], v[212:215], v[0:15]
	ds_read_b64_tr_b16 v[212:213], v189 offset:0x200
	ds_read_b64_tr_b16 v[214:215], v189 offset:0xa00
	v_mfma_f32_32x32x16_bf16 v[0:15], v[238:241], v[216:219], v[0:15]
	ds_read_b64_tr_b16 v[216:217], v189 offset:0x1200
	ds_read_b64_tr_b16 v[218:219], v189 offset:0x1a00
	s_nop 0
	v_max3_f32 v250, v80, v81, v82
	v_max3_f32 v250, v250, v83, v84
	v_max3_f32 v250, v250, v85, v86
	v_max3_f32 v250, v250, v87, v88
	v_max3_f32 v250, v250, v89, v90
	v_max3_f32 v250, v250, v91, v92
	s_waitcnt lgkmcnt(4)
	v_mfma_f32_32x32x16_bf16 v[0:15], v[242:245], v[220:223], v[0:15]
	ds_read_b64_tr_b16 v[220:221], v189 offset:0x2200
	ds_read_b64_tr_b16 v[222:223], v189 offset:0x2a00
	v_max3_f32 v250, v250, v93, v94
	v_max3_f32 v250, v250, v95, v64
	v_max3_f32 v250, v250, v65, v66
	v_max3_f32 v250, v250, v67, v68
	v_max3_f32 v250, v250, v69, v70
	v_max3_f32 v250, v250, v71, v72
	v_mfma_f32_32x32x16_bf16 v[0:15], v[246:249], v[224:227], v[0:15]
	ds_read_b64_tr_b16 v[224:225], v189 offset:0x3200
	ds_read_b64_tr_b16 v[226:227], v189 offset:0x3a00
	v_max3_f32 v250, v250, v73, v74
	v_max3_f32 v250, v250, v75, v76
	v_max3_f32 v250, v250, v77, v78
	v_max_f32_e32 v250, v250, v79
	v_mov_b32_e32 v251, v250
	s_waitcnt lgkmcnt(4)
	v_mfma_f32_32x32x16_bf16 v[16:31], v[234:237], v[212:215], v[16:31]
	ds_read_b64_tr_b16 v[212:213], v189 offset:0x400
	ds_read_b64_tr_b16 v[214:215], v189 offset:0xc00
	v_permlane32_swap_b32_e32 v250, v251
	v_max_f32_e32 v251, v250, v251
	v_cmp_ge_f32_e32 vcc, s63, v251
	s_cmp_eq_u64 vcc, exec
	s_cbranch_scc0 .Lda1_rare1
.Lda1_cont1:
	v_mfma_f32_32x32x16_bf16 v[16:31], v[238:241], v[216:219], v[16:31]
	ds_read_b64_tr_b16 v[216:217], v189 offset:0x1400
	ds_read_b64_tr_b16 v[218:219], v189 offset:0x1c00
	v_exp_f32_e32 v80, v80
	v_exp_f32_e32 v81, v81
	v_add_f32_e32 v252, 0, v80
	v_exp_f32_e32 v82, v82
	v_add_f32_e32 v252, v81, v252
	v_exp_f32_e32 v83, v83
	v_add_f32_e32 v252, v82, v252
	s_waitcnt lgkmcnt(4)
	v_mfma_f32_32x32x16_bf16 v[16:31], v[242:245], v[220:223], v[16:31]
	ds_read_b64_tr_b16 v[220:221], v189 offset:0x2400
	ds_read_b64_tr_b16 v[222:223], v189 offset:0x2c00
	v_cvt_pk_bf16_f32 v136, v80, v81
	v_exp_f32_e32 v84, v84
	v_add_f32_e32 v252, v83, v252
	v_exp_f32_e32 v85, v85
	v_add_f32_e32 v252, v84, v252
	v_cvt_pk_bf16_f32 v137, v82, v83
	v_exp_f32_e32 v86, v86
	v_add_f32_e32 v252, v85, v252
	v_mfma_f32_32x32x16_bf16 v[16:31], v[246:249], v[224:227], v[16:31]
	ds_read_b64_tr_b16 v[224:225], v189 offset:0x3400
	ds_read_b64_tr_b16 v[226:227], v189 offset:0x3c00
	s_waitcnt vmcnt(0)
	s_sub_i32 s11, s25, 0x10000
	v_add_u32_e32 v155, s101, v173
	v_exp_f32_e32 v87, v87
	v_add_f32_e32 v252, v86, v252
	v_cvt_pk_bf16_f32 v138, v84, v85
	v_exp_f32_e32 v88, v88
	v_add_f32_e32 v252, v87, v252
	v_exp_f32_e32 v89, v89
	v_add_f32_e32 v252, v88, v252
	v_cvt_pk_bf16_f32 v139, v86, v87
	s_waitcnt lgkmcnt(4)
	v_mfma_f32_32x32x16_bf16 v[32:47], v[234:237], v[212:215], v[32:47]
	ds_read_b64_tr_b16 v[212:213], v189 offset:0x600
	ds_read_b64_tr_b16 v[214:215], v189 offset:0xe00
	ds_write_b128 v155, v[128:131]
	v_exp_f32_e32 v90, v90
	v_add_f32_e32 v252, v89, v252
	v_exp_f32_e32 v91, v91
	v_permlane32_swap_b32_e32 v136, v138
	v_permlane32_swap_b32_e32 v137, v139
	v_add_f32_e32 v252, v90, v252
	v_cvt_pk_bf16_f32 v140, v88, v89
	v_exp_f32_e32 v92, v92
	v_mfma_f32_32x32x16_bf16 v[32:47], v[238:241], v[216:219], v[32:47]
	ds_read_b64_tr_b16 v[216:217], v189 offset:0x1600
	ds_read_b64_tr_b16 v[218:219], v189 offset:0x1e00
	ds_write_b128 v155, v[112:115] offset:16384
	v_add_u32_e32 v155, s101, v174
	v_add_f32_e32 v252, v91, v252
	v_exp_f32_e32 v93, v93
	v_add_f32_e32 v252, v92, v252
	v_cvt_pk_bf16_f32 v141, v90, v91
	v_exp_f32_e32 v94, v94
	v_add_f32_e32 v252, v93, v252
	v_exp_f32_e32 v95, v95
	v_add_f32_e32 v252, v94, v252
	s_waitcnt lgkmcnt(6)
	v_mfma_f32_32x32x16_bf16 v[32:47], v[242:245], v[220:223], v[32:47]
	ds_read_b64_tr_b16 v[220:221], v189 offset:0x2600
	ds_read_b64_tr_b16 v[222:223], v189 offset:0x2e00
	ds_write_b128 v155, v[124:127]
	v_cvt_pk_bf16_f32 v142, v92, v93
	v_exp_f32_e32 v64, v64
	v_add_f32_e32 v252, v95, v252
	v_exp_f32_e32 v65, v65
	v_add_f32_e32 v252, v64, v252
	v_cvt_pk_bf16_f32 v143, v94, v95
	v_exp_f32_e32 v66, v66
	v_add_f32_e32 v252, v65, v252
	v_mfma_f32_32x32x16_bf16 v[32:47], v[246:249], v[224:227], v[32:47]
	ds_read_b64_tr_b16 v[224:225], v189 offset:0x3600
	ds_read_b64_tr_b16 v[226:227], v189 offset:0x3e00
	ds_write_b128 v155, v[116:119] offset:16384
	v_add_u32_e32 v155, s11, v175
	v_exp_f32_e32 v67, v67
	v_permlane32_swap_b32_e32 v140, v142
	v_permlane32_swap_b32_e32 v141, v143
	v_add_f32_e32 v252, v66, v252
	v_cvt_pk_bf16_f32 v144, v64, v65
	v_exp_f32_e32 v68, v68
	v_add_f32_e32 v252, v67, v252
	v_exp_f32_e32 v69, v69
	s_waitcnt lgkmcnt(7)
	v_mfma_f32_32x32x16_bf16 v[48:63], v[234:237], v[212:215], v[48:63]
	ds_write_b128 v155, v[132:135]
	v_add_f32_e32 v252, v68, v252
	v_cvt_pk_bf16_f32 v145, v66, v67
	v_exp_f32_e32 v70, v70
	v_add_f32_e32 v252, v69, v252
	v_exp_f32_e32 v71, v71
	v_add_f32_e32 v252, v70, v252
	v_cvt_pk_bf16_f32 v146, v68, v69
	v_exp_f32_e32 v72, v72
	v_mfma_f32_32x32x16_bf16 v[48:63], v[238:241], v[216:219], v[48:63]
	ds_write_b128 v155, v[120:123] offset:8192
	v_add_f32_e32 v252, v71, v252
	v_exp_f32_e32 v73, v73
	v_add_f32_e32 v252, v72, v252
	v_cvt_pk_bf16_f32 v147, v70, v71
	v_exp_f32_e32 v74, v74
	v_add_f32_e32 v252, v73, v252
	v_exp_f32_e32 v75, v75
	v_permlane32_swap_b32_e32 v144, v146
	s_waitcnt lgkmcnt(3)
	v_mfma_f32_32x32x16_bf16 v[48:63], v[242:245], v[220:223], v[48:63]
	v_permlane32_swap_b32_e32 v145, v147
	v_add_f32_e32 v252, v74, v252
	v_cvt_pk_bf16_f32 v148, v72, v73
	v_exp_f32_e32 v76, v76
	v_add_f32_e32 v252, v75, v252
	v_exp_f32_e32 v77, v77
	v_add_f32_e32 v252, v76, v252
	v_cvt_pk_bf16_f32 v149, v74, v75
	v_exp_f32_e32 v78, v78
	v_mfma_f32_32x32x16_bf16 v[48:63], v[246:249], v[224:227], v[48:63]
	ds_read_b128 v[228:231], v193 offset:8192
	ds_read_b128 v[224:227], v193 offset:12288
	v_add_f32_e32 v252, v77, v252
	v_exp_f32_e32 v79, v79
	v_add_f32_e32 v252, v78, v252
	v_cvt_pk_bf16_f32 v150, v76, v77
	v_add_f32_e32 v252, v79, v252
	v_cvt_pk_bf16_f32 v151, v78, v79
	v_fma_f32 v192, v192, v253, v252
	s_nop 0
	s_nop 0
	v_permlane32_swap_b32_e32 v148, v150
	v_permlane32_swap_b32_e32 v149, v151

.LBB0_66:
	s_waitcnt lgkmcnt(0)
	s_barrier
	v_add_u32_e32 v189, s100, v153
	s_waitcnt lgkmcnt(1)
	v_mfma_f32_32x32x16_bf16 v[80:95], v[228:231], v[108:111], v[196:211]
	ds_read_b128 v[228:231], v194 offset:8192
	s_waitcnt lgkmcnt(1)
	v_mfma_f32_32x32x16_bf16 v[64:79], v[224:227], v[108:111], v[196:211]
	ds_read_b128 v[224:227], v194 offset:12288
	s_waitcnt lgkmcnt(1)
	v_mfma_f32_32x32x16_bf16 v[80:95], v[228:231], v[104:107], v[80:95]
	ds_read_b128 v[228:231], v232 offset:8192
	s_waitcnt lgkmcnt(1)
	v_mfma_f32_32x32x16_bf16 v[64:79], v[224:227], v[104:107], v[64:79]
	ds_read_b128 v[224:227], v232 offset:12288
	s_waitcnt lgkmcnt(1)
	v_mfma_f32_32x32x16_bf16 v[80:95], v[228:231], v[100:103], v[80:95]
	ds_read_b128 v[228:231], v233 offset:8192
	s_waitcnt lgkmcnt(1)
	v_mfma_f32_32x32x16_bf16 v[64:79], v[224:227], v[100:103], v[64:79]
	ds_read_b128 v[224:227], v233 offset:12288
	ds_read_b64_tr_b16 v[212:213], v189 offset:0
	ds_read_b64_tr_b16 v[214:215], v189 offset:0x800
	ds_read_b64_tr_b16 v[216:217], v189 offset:0x1000
	ds_read_b64_tr_b16 v[218:219], v189 offset:0x1800
	ds_read_b64_tr_b16 v[220:221], v189 offset:0x2000
	ds_read_b64_tr_b16 v[222:223], v189 offset:0x2800
	s_waitcnt lgkmcnt(7)
	v_mfma_f32_32x32x16_bf16 v[80:95], v[228:231], v[96:99], v[80:95]
	s_waitcnt lgkmcnt(6)
	v_mfma_f32_32x32x16_bf16 v[64:79], v[224:227], v[96:99], v[64:79]
	ds_read_b64_tr_b16 v[224:225], v189 offset:0x3000
	ds_read_b64_tr_b16 v[226:227], v189 offset:0x3800
	s_cmp_eq_u32 s67, s22
	s_cbranch_scc1 .LBB0_61
	s_add_u32 s10, s22, 0xc0000
	s_cmp_eq_u32 s67, s10
	s_cbranch_scc1 .Lda1_sl_last
	s_add_u32 s10, s77, s22
	s_addc_u32 s11, s66, s23
	s_add_u32 s48, s10, 0x12783400
	s_addc_u32 s49, s11, 0
	s_add_u32 s50, s77, s22
	s_addc_u32 s51, s66, s23
	s_add_u32 s50, s50, 0x12782c00
	s_addc_u32 s51, s51, 0
	global_load_dwordx4 v[128:131], v156, s[48:49]
	global_load_dwordx4 v[124:127], v158, s[48:49]
	global_load_dwordx4 v[132:135], v160, s[50:51]
	global_load_dwordx4 v[112:115], v166, s[48:49]
	global_load_dwordx4 v[116:119], v164, s[48:49]
	global_load_dwordx4 v[120:123], v162, s[50:51]
	s_branch .LBB0_61

.LBB0_61:
	s_waitcnt lgkmcnt(4)
	v_mfma_f32_32x32x16_bf16 v[0:15], v[136:139], v[212:215], v[0:15]
	ds_read_b64_tr_b16 v[212:213], v189 offset:0x200
	ds_read_b64_tr_b16 v[214:215], v189 offset:0xa00
	v_mfma_f32_32x32x16_bf16 v[0:15], v[140:143], v[216:219], v[0:15]
	ds_read_b64_tr_b16 v[216:217], v189 offset:0x1200
	ds_read_b64_tr_b16 v[218:219], v189 offset:0x1a00
	s_nop 0
	v_max3_f32 v250, v80, v81, v82
	v_max3_f32 v250, v250, v83, v84
	v_max3_f32 v250, v250, v85, v86
	v_max3_f32 v250, v250, v87, v88
	v_max3_f32 v250, v250, v89, v90
	v_max3_f32 v250, v250, v91, v92
	s_waitcnt lgkmcnt(4)
	v_mfma_f32_32x32x16_bf16 v[0:15], v[144:147], v[220:223], v[0:15]
	ds_read_b64_tr_b16 v[220:221], v189 offset:0x2200
	ds_read_b64_tr_b16 v[222:223], v189 offset:0x2a00
	v_max3_f32 v250, v250, v93, v94
	v_max3_f32 v250, v250, v95, v64
	v_max3_f32 v250, v250, v65, v66
	v_max3_f32 v250, v250, v67, v68
	v_max3_f32 v250, v250, v69, v70
	v_max3_f32 v250, v250, v71, v72
	v_mfma_f32_32x32x16_bf16 v[0:15], v[148:151], v[224:227], v[0:15]
	ds_read_b64_tr_b16 v[224:225], v189 offset:0x3200
	ds_read_b64_tr_b16 v[226:227], v189 offset:0x3a00
	v_max3_f32 v250, v250, v73, v74
	v_max3_f32 v250, v250, v75, v76
	v_max3_f32 v250, v250, v77, v78
	v_max_f32_e32 v250, v250, v79
	v_mov_b32_e32 v251, v250
	s_waitcnt lgkmcnt(4)
	v_mfma_f32_32x32x16_bf16 v[16:31], v[136:139], v[212:215], v[16:31]
	ds_read_b64_tr_b16 v[212:213], v189 offset:0x400
	ds_read_b64_tr_b16 v[214:215], v189 offset:0xc00
	v_permlane32_swap_b32_e32 v250, v251
	v_max_f32_e32 v251, v250, v251
	v_cmp_ge_f32_e32 vcc, s63, v251
	s_cmp_eq_u64 vcc, exec
	s_cbranch_scc0 .Lda1_rare2
.Lda1_cont2:
	v_mfma_f32_32x32x16_bf16 v[16:31], v[140:143], v[216:219], v[16:31]
	ds_read_b64_tr_b16 v[216:217], v189 offset:0x1400
	ds_read_b64_tr_b16 v[218:219], v189 offset:0x1c00
	v_exp_f32_e32 v80, v80
	v_exp_f32_e32 v81, v81
	v_add_f32_e32 v252, 0, v80
	v_exp_f32_e32 v82, v82
	v_add_f32_e32 v252, v81, v252
	v_exp_f32_e32 v83, v83
	v_add_f32_e32 v252, v82, v252
	s_waitcnt lgkmcnt(4)
	v_mfma_f32_32x32x16_bf16 v[16:31], v[144:147], v[220:223], v[16:31]
	ds_read_b64_tr_b16 v[220:221], v189 offset:0x2400
	ds_read_b64_tr_b16 v[222:223], v189 offset:0x2c00
	v_cvt_pk_bf16_f32 v234, v80, v81
	v_exp_f32_e32 v84, v84
	v_add_f32_e32 v252, v83, v252
	v_exp_f32_e32 v85, v85
	v_add_f32_e32 v252, v84, v252
	v_cvt_pk_bf16_f32 v235, v82, v83
	v_exp_f32_e32 v86, v86
	v_add_f32_e32 v252, v85, v252
	v_mfma_f32_32x32x16_bf16 v[16:31], v[148:151], v[224:227], v[16:31]
	ds_read_b64_tr_b16 v[224:225], v189 offset:0x3400
	ds_read_b64_tr_b16 v[226:227], v189 offset:0x3c00
	v_exp_f32_e32 v87, v87
	v_add_f32_e32 v252, v86, v252
	v_cvt_pk_bf16_f32 v236, v84, v85
	v_exp_f32_e32 v88, v88
	v_add_f32_e32 v252, v87, v252
	v_exp_f32_e32 v89, v89
	v_add_f32_e32 v252, v88, v252
	v_cvt_pk_bf16_f32 v237, v86, v87
	s_waitcnt lgkmcnt(4)
	v_mfma_f32_32x32x16_bf16 v[32:47], v[136:139], v[212:215], v[32:47]
	ds_read_b64_tr_b16 v[212:213], v189 offset:0x600
	ds_read_b64_tr_b16 v[214:215], v189 offset:0xe00
	v_exp_f32_e32 v90, v90
	v_add_f32_e32 v252, v89, v252
	v_exp_f32_e32 v91, v91
	v_permlane32_swap_b32_e32 v234, v236
	v_permlane32_swap_b32_e32 v235, v237
	v_add_f32_e32 v252, v90, v252
	v_cvt_pk_bf16_f32 v238, v88, v89
	v_exp_f32_e32 v92, v92
	v_mfma_f32_32x32x16_bf16 v[32:47], v[140:143], v[216:219], v[32:47]
	ds_read_b64_tr_b16 v[216:217], v189 offset:0x1600
	ds_read_b64_tr_b16 v[218:219], v189 offset:0x1e00
	v_add_f32_e32 v252, v91, v252
	v_exp_f32_e32 v93, v93
	v_add_f32_e32 v252, v92, v252
	v_cvt_pk_bf16_f32 v239, v90, v91
	v_exp_f32_e32 v94, v94
	v_add_f32_e32 v252, v93, v252
	v_exp_f32_e32 v95, v95
	v_add_f32_e32 v252, v94, v252
	s_waitcnt lgkmcnt(4)
	v_mfma_f32_32x32x16_bf16 v[32:47], v[144:147], v[220:223], v[32:47]
	ds_read_b64_tr_b16 v[220:221], v189 offset:0x2600
	ds_read_b64_tr_b16 v[222:223], v189 offset:0x2e00
	v_cvt_pk_bf16_f32 v240, v92, v93
	v_exp_f32_e32 v64, v64
	v_add_f32_e32 v252, v95, v252
	v_exp_f32_e32 v65, v65
	v_add_f32_e32 v252, v64, v252
	v_cvt_pk_bf16_f32 v241, v94, v95
	v_exp_f32_e32 v66, v66
	v_add_f32_e32 v252, v65, v252
	v_mfma_f32_32x32x16_bf16 v[32:47], v[148:151], v[224:227], v[32:47]
	ds_read_b64_tr_b16 v[224:225], v189 offset:0x3600
	ds_read_b64_tr_b16 v[226:227], v189 offset:0x3e00
	v_exp_f32_e32 v67, v67
	v_permlane32_swap_b32_e32 v238, v240
	v_permlane32_swap_b32_e32 v239, v241
	v_add_f32_e32 v252, v66, v252
	v_cvt_pk_bf16_f32 v242, v64, v65
	v_exp_f32_e32 v68, v68
	v_add_f32_e32 v252, v67, v252
	v_exp_f32_e32 v69, v69
	s_waitcnt lgkmcnt(4)
	v_mfma_f32_32x32x16_bf16 v[48:63], v[136:139], v[212:215], v[48:63]
	v_add_f32_e32 v252, v68, v252
	v_cvt_pk_bf16_f32 v243, v66, v67
	v_exp_f32_e32 v70, v70
	v_add_f32_e32 v252, v69, v252
	v_exp_f32_e32 v71, v71
	v_add_f32_e32 v252, v70, v252
	v_cvt_pk_bf16_f32 v244, v68, v69
	v_exp_f32_e32 v72, v72
	v_mfma_f32_32x32x16_bf16 v[48:63], v[140:143], v[216:219], v[48:63]
	v_add_f32_e32 v252, v71, v252
	v_exp_f32_e32 v73, v73
	v_add_f32_e32 v252, v72, v252
	v_cvt_pk_bf16_f32 v245, v70, v71
	v_exp_f32_e32 v74, v74
	v_add_f32_e32 v252, v73, v252
	v_exp_f32_e32 v75, v75
	v_permlane32_swap_b32_e32 v242, v244
	s_waitcnt lgkmcnt(0)
	v_mfma_f32_32x32x16_bf16 v[48:63], v[144:147], v[220:223], v[48:63]
	v_permlane32_swap_b32_e32 v243, v245
	v_add_f32_e32 v252, v74, v252
	v_cvt_pk_bf16_f32 v246, v72, v73
	v_exp_f32_e32 v76, v76
	v_add_f32_e32 v252, v75, v252
	v_exp_f32_e32 v77, v77
	v_add_f32_e32 v252, v76, v252
	v_cvt_pk_bf16_f32 v247, v74, v75
	v_exp_f32_e32 v78, v78
	v_mfma_f32_32x32x16_bf16 v[48:63], v[148:151], v[224:227], v[48:63]
	s_sub_i32 s10, 0x20800, s100
	s_sub_i32 s10, s10, s101
	s_sub_i32 s11, 0x44800, s89
	s_sub_i32 s11, s11, s25
	s_mov_b32 s100, s101
	s_mov_b32 s101, s10
	s_mov_b32 s89, s25
	s_mov_b32 s25, s11
	v_add_u32_e32 v193, s89, v182
	v_add_u32_e32 v194, s89, v186
	v_add_u32_e32 v232, s89, v187
	v_add_u32_e32 v233, s89, v188
	ds_read_b128 v[228:231], v193
	ds_read_b128 v[224:227], v193 offset:4096
	v_add_f32_e32 v252, v77, v252
	v_exp_f32_e32 v79, v79
	v_add_f32_e32 v252, v78, v252
	v_cvt_pk_bf16_f32 v248, v76, v77
	v_add_f32_e32 v252, v79, v252
	v_cvt_pk_bf16_f32 v249, v78, v79
	v_fma_f32 v192, v192, v253, v252
	s_nop 0
	s_nop 0
	v_permlane32_swap_b32_e32 v246, v248
	v_permlane32_swap_b32_e32 v247, v249
.LBB0_67:
	v_cmp_gt_f32_e32 vcc, 1.0, v253
	s_cbranch_vccz .LBB0_71
	s_and_saveexec_b64 s[10:11], s[8:9]
	ds_write_b32 v191, v253 offset:128
	s_or_b64 exec, exec, s[10:11]
	s_waitcnt lgkmcnt(0)
	v_add_u32_e32 v251, s59, v152
	ds_read_b128 v[212:215], v251 offset:224
	ds_read_b128 v[216:219], v251 offset:192
	ds_read_b128 v[220:223], v251 offset:160
	ds_read_b128 v[224:227], v251 offset:128
	s_waitcnt lgkmcnt(3)
	v_pk_mul_f32 v[12:13], v[12:13], v[212:213]
	s_waitcnt lgkmcnt(2)
	v_pk_mul_f32 v[8:9], v[8:9], v[216:217]
	s_waitcnt lgkmcnt(1)
	v_pk_mul_f32 v[4:5], v[4:5], v[220:221]
	v_pk_mul_f32 v[14:15], v[14:15], v[214:215]
	v_pk_mul_f32 v[10:11], v[10:11], v[218:219]
	v_pk_mul_f32 v[6:7], v[6:7], v[222:223]
	s_waitcnt lgkmcnt(0)
	v_pk_mul_f32 v[2:3], v[2:3], v[226:227]
	v_pk_mul_f32 v[0:1], v[0:1], v[224:225]
	v_pk_mul_f32 v[28:29], v[28:29], v[212:213]
	v_pk_mul_f32 v[24:25], v[24:25], v[216:217]
	v_pk_mul_f32 v[20:21], v[20:21], v[220:221]
	v_pk_mul_f32 v[30:31], v[30:31], v[214:215]
	v_pk_mul_f32 v[26:27], v[26:27], v[218:219]
	v_pk_mul_f32 v[22:23], v[22:23], v[222:223]
	v_pk_mul_f32 v[18:19], v[18:19], v[226:227]
	v_pk_mul_f32 v[16:17], v[16:17], v[224:225]
	v_pk_mul_f32 v[44:45], v[44:45], v[212:213]
	v_pk_mul_f32 v[40:41], v[40:41], v[216:217]
	v_pk_mul_f32 v[36:37], v[36:37], v[220:221]
	v_pk_mul_f32 v[46:47], v[46:47], v[214:215]
	v_pk_mul_f32 v[42:43], v[42:43], v[218:219]
	v_pk_mul_f32 v[38:39], v[38:39], v[222:223]
	v_pk_mul_f32 v[34:35], v[34:35], v[226:227]
	v_pk_mul_f32 v[32:33], v[32:33], v[224:225]
	v_pk_mul_f32 v[60:61], v[60:61], v[212:213]
	v_pk_mul_f32 v[56:57], v[56:57], v[216:217]
	v_pk_mul_f32 v[52:53], v[52:53], v[220:221]
	v_pk_mul_f32 v[62:63], v[62:63], v[214:215]
	v_pk_mul_f32 v[58:59], v[58:59], v[218:219]
	v_pk_mul_f32 v[54:55], v[54:55], v[222:223]
	v_pk_mul_f32 v[50:51], v[50:51], v[226:227]
	v_pk_mul_f32 v[48:49], v[48:49], v[224:225]
	v_mov_b32_e32 v253, 1.0
	ds_read_b128 v[228:231], v193
	ds_read_b128 v[224:227], v193 offset:4096
.LBB0_71:
	s_add_u32 s22, s22, 0xc0000
	s_addc_u32 s23, s23, 0
	s_cmp_eq_u32 s88, s22
	s_cbranch_scc1 .LBB0_76
	s_branch .LBB0_55

.LBB0_90:
	v_exp_f32_e32 v238, v80
	v_exp_f32_e32 v240, v81
	v_exp_f32_e32 v241, v82
	v_exp_f32_e32 v243, v83
	v_exp_f32_e32 v244, v84
	v_exp_f32_e32 v133, v64
	v_exp_f32_e32 v132, v66
	v_add_f32_e32 v64, 0, v238
	v_add_f32_e32 v66, 0, v145
	v_exp_f32_e32 v245, v85
	v_add_f32_e32 v64, v240, v64
	v_add_f32_e32 v66, v146, v66
	v_exp_f32_e32 v239, v86
	v_add_f32_e32 v64, v241, v64
	v_add_f32_e32 v66, v147, v66
	v_exp_f32_e32 v242, v87
	v_add_f32_e32 v64, v243, v64
	v_add_f32_e32 v66, v148, v66
	v_exp_f32_e32 v234, v88
	v_add_f32_e32 v64, v244, v64
	v_add_f32_e32 v66, v149, v66
	v_exp_f32_e32 v235, v89
	v_add_f32_e32 v64, v245, v64
	v_add_f32_e32 v66, v150, v66
	v_exp_f32_e32 v236, v90
	v_add_f32_e32 v64, v239, v64
	v_add_f32_e32 v66, v151, v66
	v_exp_f32_e32 v237, v91
	v_add_f32_e32 v64, v242, v64
	v_add_f32_e32 v66, v155, v66
	v_exp_f32_e32 v230, v92
	v_add_f32_e32 v64, v234, v64
	v_add_f32_e32 v66, v168, v66
	v_exp_f32_e32 v232, v93
	v_add_f32_e32 v64, v235, v64
	v_add_f32_e32 v66, v169, v66
	v_exp_f32_e32 v231, v94
	v_add_f32_e32 v64, v236, v64
	v_add_f32_e32 v66, v170, v66
	v_exp_f32_e32 v233, v95
	v_add_f32_e32 v64, v237, v64
	v_add_f32_e32 v66, v171, v66
	v_add_f32_e32 v64, v230, v64
	v_add_f32_e32 v66, v191, v66
	v_exp_f32_e32 v226, v65
	v_add_f32_e32 v64, v232, v64
	v_add_f32_e32 v66, v192, v66
	v_add_f32_e32 v64, v231, v64
	v_add_f32_e32 v66, v195, v66
	v_exp_f32_e32 v134, v67
	v_add_f32_e32 v64, v233, v64
	v_add_f32_e32 v66, v196, v66
	v_exp_f32_e32 v135, v68
	v_add_f32_e32 v64, v133, v64
	v_add_f32_e32 v66, v197, v66
	v_exp_f32_e32 v227, v69
	v_add_f32_e32 v64, v226, v64
	v_add_f32_e32 v66, v198, v66
	v_exp_f32_e32 v228, v70
	v_add_f32_e32 v64, v132, v64
	v_add_f32_e32 v66, v199, v66
	v_exp_f32_e32 v229, v71
	v_add_f32_e32 v64, v134, v64
	v_add_f32_e32 v66, v200, v66
	v_exp_f32_e32 v124, v72
	v_add_f32_e32 v64, v135, v64
	v_add_f32_e32 v66, v201, v66
	v_exp_f32_e32 v125, v73
	v_add_f32_e32 v64, v227, v64
	v_add_f32_e32 v66, v211, v66
	v_exp_f32_e32 v126, v74
	v_add_f32_e32 v64, v228, v64
	v_add_f32_e32 v66, v212, v66
	v_exp_f32_e32 v127, v75
	v_add_f32_e32 v64, v229, v64
	v_add_f32_e32 v66, v213, v66
	v_exp_f32_e32 v128, v76
	v_add_f32_e32 v64, v124, v64
	v_add_f32_e32 v66, v214, v66
	v_exp_f32_e32 v129, v77
	v_add_f32_e32 v64, v125, v64
	v_add_f32_e32 v66, v215, v66
	v_exp_f32_e32 v130, v78
	v_add_f32_e32 v64, v126, v64
	v_add_f32_e32 v66, v216, v66
	v_exp_f32_e32 v131, v79
	v_add_f32_e32 v64, v127, v64
	v_add_f32_e32 v66, v217, v66
	s_add_u32 s38, s46, 0x80
	v_add_f32_e32 v64, v128, v64
	v_add_f32_e32 v66, v218, v66
	s_addc_u32 s39, s47, 0
	v_mad_i64_i32 v[156:157], s[8:9], v138, s73, 0
	v_mad_i64_i32 v[158:159], s[8:9], v139, s73, 0
	v_mad_i64_i32 v[160:161], s[8:9], v140, s73, 0
	v_mad_i64_i32 v[162:163], s[8:9], v142, s73, 0
	v_mad_i64_i32 v[164:165], s[8:9], v143, s73, 0
	v_mad_i64_i32 v[166:167], s[8:9], v144, s73, 0
	v_add_f32_e32 v64, v129, v64
	v_add_f32_e32 v66, v219, v66
	s_cmp_lg_u32 0, -1
	v_add_f32_e32 v64, v130, v64
	v_add_f32_e32 v66, v220, v66
	s_cselect_b32 s8, 0, 0
	v_add_f32_e32 v194, v131, v64
	v_bfe_u32 v64, v137, 4, 4
	v_bfe_u32 v65, v137, 3, 4
	v_add_f32_e32 v66, v221, v66
	s_addk_i32 s8, 0x4000
	v_add_f32_e32 v192, 0, v66
	v_add_u32_e32 v195, s8, v188
	v_cmp_gt_u32_e64 s[8:9], 32, v141
	v_lshl_add_u32 v191, v136, 2, s59
	v_mul_u32_u24_e32 v168, 0x1800, v64
	v_mov_b32_e32 v169, v181
	v_mul_u32_u24_e32 v170, 0x1800, v65
	v_mov_b32_e32 v171, v181
	s_mov_b32 s23, 1
	s_mov_b64 s[40:41], 0
	s_waitcnt lgkmcnt(0)
	s_barrier
	s_mov_b32 s100, 0x8000
	s_mov_b32 s101, 0x18800
	s_mov_b32 s46, 0x14000
	s_mov_b32 s23, 0x20800
	v_fma_f32 v192, v192, v193, v194
	v_cvt_pk_bf16_f32 v250, v238, v240
	v_cvt_pk_bf16_f32 v251, v241, v243
	v_cvt_pk_bf16_f32 v252, v244, v245
	v_cvt_pk_bf16_f32 v253, v239, v242
	v_cvt_pk_bf16_f32 v238, v234, v235
	v_cvt_pk_bf16_f32 v239, v236, v237
	v_cvt_pk_bf16_f32 v240, v230, v232
	v_cvt_pk_bf16_f32 v241, v231, v233
	v_cvt_pk_bf16_f32 v242, v133, v226
	v_cvt_pk_bf16_f32 v243, v132, v134
	v_cvt_pk_bf16_f32 v244, v135, v227
	v_cvt_pk_bf16_f32 v245, v228, v229
	v_cvt_pk_bf16_f32 v246, v124, v125
	v_cvt_pk_bf16_f32 v247, v126, v127
	v_cvt_pk_bf16_f32 v248, v128, v129
	v_cvt_pk_bf16_f32 v249, v130, v131
	s_nop 1
	v_permlane32_swap_b32_e32 v250, v252
	v_permlane32_swap_b32_e32 v251, v253
	v_permlane32_swap_b32_e32 v238, v240
	v_permlane32_swap_b32_e32 v239, v241
	v_permlane32_swap_b32_e32 v242, v244
	v_permlane32_swap_b32_e32 v243, v245
	v_permlane32_swap_b32_e32 v246, v248
	v_permlane32_swap_b32_e32 v247, v249
	v_mov_b32_e32 v234, v250
	v_mov_b32_e32 v235, v251
	v_mov_b32_e32 v236, v252
	v_mov_b32_e32 v237, v253
	v_xor_b32_e32 v196, 0x80000000, v190
	v_mov_b32_e32 v197, v196
	v_mov_b32_e32 v198, v196
	v_mov_b32_e32 v199, v196
	v_mov_b32_e32 v200, v196
	v_mov_b32_e32 v201, v196
	v_mov_b32_e32 v202, v196
	v_mov_b32_e32 v203, v196
	v_mov_b32_e32 v204, v196
	v_mov_b32_e32 v205, v196
	v_mov_b32_e32 v206, v196
	v_mov_b32_e32 v207, v196
	v_mov_b32_e32 v208, v196
	v_mov_b32_e32 v209, v196
	v_mov_b32_e32 v210, v196
	v_mov_b32_e32 v211, v196
	v_mov_b32_e32 v253, 1.0
	v_add_u32_e32 v156, v156, v180
	v_add_u32_e32 v158, v158, v180
	v_add_u32_e32 v160, v160, v154
	v_add_u32_e32 v162, v162, v154
	v_add_u32_e32 v164, v164, v180
	v_add_u32_e32 v166, v166, v180
	v_add_u32_e32 v168, v168, v180
	v_add_u32_e32 v170, v170, v154
	v_add_u32_e32 v193, s46, v175
	v_add_u32_e32 v194, s46, v182
	v_add_u32_e32 v232, s46, v186
	v_add_u32_e32 v233, s46, v187
	ds_read_b128 v[228:231], v193
	ds_read_b128 v[224:227], v193 offset:4096
	s_cmp_eq_u32 s67, s40
	s_cbranch_scc1 .Lda2_sl_laste
	s_add_u32 s10, s77, s40
	s_addc_u32 s11, s66, s41
	s_add_u32 s42, s10, 0x126c3400
	s_addc_u32 s43, s11, 0
	s_add_u32 s25, s77, s40
	s_addc_u32 s45, s66, s41
	s_add_u32 s44, s25, 0x126c2c80
	s_addc_u32 s45, s45, 0
	global_load_dwordx4 v[128:131], v156, s[42:43]
	global_load_dwordx4 v[124:127], v158, s[42:43]
	global_load_dwordx4 v[132:135], v160, s[44:45]
	global_load_dwordx4 v[112:115], v166, s[42:43]
	global_load_dwordx4 v[116:119], v164, s[42:43]
	global_load_dwordx4 v[120:123], v162, s[44:45]
	s_branch .Lda2_entry_sl

.Lda2_cont1:
	v_mfma_f32_32x32x16_bf16 v[16:31], v[238:241], v[216:219], v[16:31]
	ds_read_b64_tr_b16 v[216:217], v189 offset:0x1400
	ds_read_b64_tr_b16 v[218:219], v189 offset:0x1c00
	v_exp_f32_e32 v80, v80
	v_exp_f32_e32 v81, v81
	v_add_f32_e32 v252, 0, v80
	v_exp_f32_e32 v82, v82
	v_add_f32_e32 v252, v81, v252
	v_exp_f32_e32 v83, v83
	v_add_f32_e32 v252, v82, v252
	s_waitcnt lgkmcnt(4)
	v_mfma_f32_32x32x16_bf16 v[16:31], v[242:245], v[220:223], v[16:31]
	ds_read_b64_tr_b16 v[220:221], v189 offset:0x2400
	ds_read_b64_tr_b16 v[222:223], v189 offset:0x2c00
	v_cvt_pk_bf16_f32 v136, v80, v81
	v_exp_f32_e32 v84, v84
	v_add_f32_e32 v252, v83, v252
	v_exp_f32_e32 v85, v85
	v_add_f32_e32 v252, v84, v252
	v_cvt_pk_bf16_f32 v137, v82, v83
	v_exp_f32_e32 v86, v86
	v_add_f32_e32 v252, v85, v252
	v_mfma_f32_32x32x16_bf16 v[16:31], v[246:249], v[224:227], v[16:31]
	ds_read_b64_tr_b16 v[224:225], v189 offset:0x3400
	ds_read_b64_tr_b16 v[226:227], v189 offset:0x3c00
	s_waitcnt vmcnt(0)
	s_sub_i32 s11, s23, 0x10000
	v_add_u32_e32 v155, s101, v178
	v_exp_f32_e32 v87, v87
	v_add_f32_e32 v252, v86, v252
	v_cvt_pk_bf16_f32 v138, v84, v85
	v_exp_f32_e32 v88, v88
	v_add_f32_e32 v252, v87, v252
	v_exp_f32_e32 v89, v89
	v_add_f32_e32 v252, v88, v252
	v_cvt_pk_bf16_f32 v139, v86, v87
	s_waitcnt lgkmcnt(4)
	v_mfma_f32_32x32x16_bf16 v[32:47], v[234:237], v[212:215], v[32:47]
	ds_read_b64_tr_b16 v[212:213], v189 offset:0x600
	ds_read_b64_tr_b16 v[214:215], v189 offset:0xe00
	ds_write_b128 v155, v[128:131]
	v_exp_f32_e32 v90, v90
	v_add_f32_e32 v252, v89, v252
	v_exp_f32_e32 v91, v91
	v_permlane32_swap_b32_e32 v136, v138
	v_permlane32_swap_b32_e32 v137, v139
	v_add_f32_e32 v252, v90, v252
	v_cvt_pk_bf16_f32 v140, v88, v89
	v_exp_f32_e32 v92, v92
	v_mfma_f32_32x32x16_bf16 v[32:47], v[238:241], v[216:219], v[32:47]
	ds_read_b64_tr_b16 v[216:217], v189 offset:0x1600
	ds_read_b64_tr_b16 v[218:219], v189 offset:0x1e00
	ds_write_b128 v155, v[112:115] offset:16384
	v_add_u32_e32 v155, s101, v179
	v_add_f32_e32 v252, v91, v252
	v_exp_f32_e32 v93, v93
	v_add_f32_e32 v252, v92, v252
	v_cvt_pk_bf16_f32 v141, v90, v91
	v_exp_f32_e32 v94, v94
	v_add_f32_e32 v252, v93, v252
	v_exp_f32_e32 v95, v95
	v_add_f32_e32 v252, v94, v252
	s_waitcnt lgkmcnt(6)
	v_mfma_f32_32x32x16_bf16 v[32:47], v[242:245], v[220:223], v[32:47]
	ds_read_b64_tr_b16 v[220:221], v189 offset:0x2600
	ds_read_b64_tr_b16 v[222:223], v189 offset:0x2e00
	ds_write_b128 v155, v[124:127]
	v_cvt_pk_bf16_f32 v142, v92, v93
	v_exp_f32_e32 v64, v64
	v_add_f32_e32 v252, v95, v252
	v_exp_f32_e32 v65, v65
	v_add_f32_e32 v252, v64, v252
	v_cvt_pk_bf16_f32 v143, v94, v95
	v_exp_f32_e32 v66, v66
	v_add_f32_e32 v252, v65, v252
	v_mfma_f32_32x32x16_bf16 v[32:47], v[246:249], v[224:227], v[32:47]
	ds_read_b64_tr_b16 v[224:225], v189 offset:0x3600
	ds_read_b64_tr_b16 v[226:227], v189 offset:0x3e00
	ds_write_b128 v155, v[116:119] offset:16384
	v_add_u32_e32 v155, s11, v177
	v_exp_f32_e32 v67, v67
	v_permlane32_swap_b32_e32 v140, v142
	v_permlane32_swap_b32_e32 v141, v143
	v_add_f32_e32 v252, v66, v252
	v_cvt_pk_bf16_f32 v144, v64, v65
	v_exp_f32_e32 v68, v68
	v_add_f32_e32 v252, v67, v252
	v_exp_f32_e32 v69, v69
	s_waitcnt lgkmcnt(7)
	v_mfma_f32_32x32x16_bf16 v[48:63], v[234:237], v[212:215], v[48:63]
	ds_write_b128 v155, v[132:135]
	v_add_f32_e32 v252, v68, v252
	v_cvt_pk_bf16_f32 v145, v66, v67
	v_exp_f32_e32 v70, v70
	v_add_f32_e32 v252, v69, v252
	v_exp_f32_e32 v71, v71
	v_add_f32_e32 v252, v70, v252
	v_cvt_pk_bf16_f32 v146, v68, v69
	v_exp_f32_e32 v72, v72
	v_mfma_f32_32x32x16_bf16 v[48:63], v[238:241], v[216:219], v[48:63]
	ds_write_b128 v155, v[120:123] offset:8192
	v_add_f32_e32 v252, v71, v252
	v_exp_f32_e32 v73, v73
	v_add_f32_e32 v252, v72, v252
	v_cvt_pk_bf16_f32 v147, v70, v71
	v_exp_f32_e32 v74, v74
	v_add_f32_e32 v252, v73, v252
	v_exp_f32_e32 v75, v75
	v_permlane32_swap_b32_e32 v144, v146
	s_waitcnt lgkmcnt(3)
	v_mfma_f32_32x32x16_bf16 v[48:63], v[242:245], v[220:223], v[48:63]
	v_permlane32_swap_b32_e32 v145, v147
	v_add_f32_e32 v252, v74, v252
	v_cvt_pk_bf16_f32 v148, v72, v73
	v_exp_f32_e32 v76, v76
	v_add_f32_e32 v252, v75, v252
	v_exp_f32_e32 v77, v77
	v_add_f32_e32 v252, v76, v252
	v_cvt_pk_bf16_f32 v149, v74, v75
	v_exp_f32_e32 v78, v78
	v_mfma_f32_32x32x16_bf16 v[48:63], v[246:249], v[224:227], v[48:63]
	ds_read_b128 v[228:231], v193 offset:8192
	ds_read_b128 v[224:227], v193 offset:12288
	v_add_f32_e32 v252, v77, v252
	v_exp_f32_e32 v79, v79
	v_add_f32_e32 v252, v78, v252
	v_cvt_pk_bf16_f32 v150, v76, v77
	v_add_f32_e32 v252, v79, v252
	v_cvt_pk_bf16_f32 v151, v78, v79
	v_fma_f32 v192, v192, v253, v252
	s_nop 0
	s_nop 0
	v_permlane32_swap_b32_e32 v148, v150
	v_permlane32_swap_b32_e32 v149, v151

.LBB0_102:
	s_waitcnt lgkmcnt(0)
	s_barrier
	v_add_u32_e32 v189, s100, v153
	s_waitcnt lgkmcnt(1)
	v_mfma_f32_32x32x16_bf16 v[80:95], v[228:231], v[108:111], v[196:211]
	ds_read_b128 v[228:231], v194 offset:8192
	s_waitcnt lgkmcnt(1)
	v_mfma_f32_32x32x16_bf16 v[64:79], v[224:227], v[108:111], v[196:211]
	ds_read_b128 v[224:227], v194 offset:12288
	s_waitcnt lgkmcnt(1)
	v_mfma_f32_32x32x16_bf16 v[80:95], v[228:231], v[104:107], v[80:95]
	ds_read_b128 v[228:231], v232 offset:8192
	s_waitcnt lgkmcnt(1)
	v_mfma_f32_32x32x16_bf16 v[64:79], v[224:227], v[104:107], v[64:79]
	ds_read_b128 v[224:227], v232 offset:12288
	s_waitcnt lgkmcnt(1)
	v_mfma_f32_32x32x16_bf16 v[80:95], v[228:231], v[100:103], v[80:95]
	ds_read_b128 v[228:231], v233 offset:8192
	s_waitcnt lgkmcnt(1)
	v_mfma_f32_32x32x16_bf16 v[64:79], v[224:227], v[100:103], v[64:79]
	ds_read_b128 v[224:227], v233 offset:12288
	ds_read_b64_tr_b16 v[212:213], v189 offset:0
	ds_read_b64_tr_b16 v[214:215], v189 offset:0x800
	ds_read_b64_tr_b16 v[216:217], v189 offset:0x1000
	ds_read_b64_tr_b16 v[218:219], v189 offset:0x1800
	ds_read_b64_tr_b16 v[220:221], v189 offset:0x2000
	ds_read_b64_tr_b16 v[222:223], v189 offset:0x2800
	s_waitcnt lgkmcnt(7)
	v_mfma_f32_32x32x16_bf16 v[80:95], v[228:231], v[96:99], v[80:95]
	s_waitcnt lgkmcnt(6)
	v_mfma_f32_32x32x16_bf16 v[64:79], v[224:227], v[96:99], v[64:79]
	ds_read_b64_tr_b16 v[224:225], v189 offset:0x3000
	ds_read_b64_tr_b16 v[226:227], v189 offset:0x3800
	s_cmp_eq_u32 s67, s40
	s_cbranch_scc1 .LBB0_97
	s_add_u32 s10, s40, 0xc0000
	s_cmp_eq_u32 s67, s10
	s_cbranch_scc1 .Lda2_sl_last
	s_add_u32 s10, s77, s40
	s_addc_u32 s11, s66, s41
	s_add_u32 s42, s10, 0x12783400
	s_addc_u32 s43, s11, 0
	s_add_u32 s25, s77, s40
	s_addc_u32 s45, s66, s41
	s_add_u32 s44, s25, 0x12782c80
	s_addc_u32 s45, s45, 0
	global_load_dwordx4 v[128:131], v156, s[42:43]
	global_load_dwordx4 v[124:127], v158, s[42:43]
	global_load_dwordx4 v[132:135], v160, s[44:45]
	global_load_dwordx4 v[112:115], v166, s[42:43]
	global_load_dwordx4 v[116:119], v164, s[42:43]
	global_load_dwordx4 v[120:123], v162, s[44:45]
	s_branch .LBB0_97

.Lda2_cont2:
	v_mfma_f32_32x32x16_bf16 v[16:31], v[140:143], v[216:219], v[16:31]
	ds_read_b64_tr_b16 v[216:217], v189 offset:0x1400
	ds_read_b64_tr_b16 v[218:219], v189 offset:0x1c00
	v_exp_f32_e32 v80, v80
	v_exp_f32_e32 v81, v81
	v_add_f32_e32 v252, 0, v80
	v_exp_f32_e32 v82, v82
	v_add_f32_e32 v252, v81, v252
	v_exp_f32_e32 v83, v83
	v_add_f32_e32 v252, v82, v252
	s_waitcnt lgkmcnt(4)
	v_mfma_f32_32x32x16_bf16 v[16:31], v[144:147], v[220:223], v[16:31]
	ds_read_b64_tr_b16 v[220:221], v189 offset:0x2400
	ds_read_b64_tr_b16 v[222:223], v189 offset:0x2c00
	v_cvt_pk_bf16_f32 v234, v80, v81
	v_exp_f32_e32 v84, v84
	v_add_f32_e32 v252, v83, v252
	v_exp_f32_e32 v85, v85
	v_add_f32_e32 v252, v84, v252
	v_cvt_pk_bf16_f32 v235, v82, v83
	v_exp_f32_e32 v86, v86
	v_add_f32_e32 v252, v85, v252
	v_mfma_f32_32x32x16_bf16 v[16:31], v[148:151], v[224:227], v[16:31]
	ds_read_b64_tr_b16 v[224:225], v189 offset:0x3400
	ds_read_b64_tr_b16 v[226:227], v189 offset:0x3c00
	v_exp_f32_e32 v87, v87
	v_add_f32_e32 v252, v86, v252
	v_cvt_pk_bf16_f32 v236, v84, v85
	v_exp_f32_e32 v88, v88
	v_add_f32_e32 v252, v87, v252
	v_exp_f32_e32 v89, v89
	v_add_f32_e32 v252, v88, v252
	v_cvt_pk_bf16_f32 v237, v86, v87
	s_waitcnt lgkmcnt(4)
	v_mfma_f32_32x32x16_bf16 v[32:47], v[136:139], v[212:215], v[32:47]
	ds_read_b64_tr_b16 v[212:213], v189 offset:0x600
	ds_read_b64_tr_b16 v[214:215], v189 offset:0xe00
	v_exp_f32_e32 v90, v90
	v_add_f32_e32 v252, v89, v252
	v_exp_f32_e32 v91, v91
	v_permlane32_swap_b32_e32 v234, v236
	v_permlane32_swap_b32_e32 v235, v237
	v_add_f32_e32 v252, v90, v252
	v_cvt_pk_bf16_f32 v238, v88, v89
	v_exp_f32_e32 v92, v92
	v_mfma_f32_32x32x16_bf16 v[32:47], v[140:143], v[216:219], v[32:47]
	ds_read_b64_tr_b16 v[216:217], v189 offset:0x1600
	ds_read_b64_tr_b16 v[218:219], v189 offset:0x1e00
	v_add_f32_e32 v252, v91, v252
	v_exp_f32_e32 v93, v93
	v_add_f32_e32 v252, v92, v252
	v_cvt_pk_bf16_f32 v239, v90, v91
	v_exp_f32_e32 v94, v94
	v_add_f32_e32 v252, v93, v252
	v_exp_f32_e32 v95, v95
	v_add_f32_e32 v252, v94, v252
	s_waitcnt lgkmcnt(4)
	v_mfma_f32_32x32x16_bf16 v[32:47], v[144:147], v[220:223], v[32:47]
	ds_read_b64_tr_b16 v[220:221], v189 offset:0x2600
	ds_read_b64_tr_b16 v[222:223], v189 offset:0x2e00
	v_cvt_pk_bf16_f32 v240, v92, v93
	v_exp_f32_e32 v64, v64
	v_add_f32_e32 v252, v95, v252
	v_exp_f32_e32 v65, v65
	v_add_f32_e32 v252, v64, v252
	v_cvt_pk_bf16_f32 v241, v94, v95
	v_exp_f32_e32 v66, v66
	v_add_f32_e32 v252, v65, v252
	v_mfma_f32_32x32x16_bf16 v[32:47], v[148:151], v[224:227], v[32:47]
	ds_read_b64_tr_b16 v[224:225], v189 offset:0x3600
	ds_read_b64_tr_b16 v[226:227], v189 offset:0x3e00
	v_exp_f32_e32 v67, v67
	v_permlane32_swap_b32_e32 v238, v240
	v_permlane32_swap_b32_e32 v239, v241
	v_add_f32_e32 v252, v66, v252
	v_cvt_pk_bf16_f32 v242, v64, v65
	v_exp_f32_e32 v68, v68
	v_add_f32_e32 v252, v67, v252
	v_exp_f32_e32 v69, v69
	s_waitcnt lgkmcnt(4)
	v_mfma_f32_32x32x16_bf16 v[48:63], v[136:139], v[212:215], v[48:63]
	v_add_f32_e32 v252, v68, v252
	v_cvt_pk_bf16_f32 v243, v66, v67
	v_exp_f32_e32 v70, v70
	v_add_f32_e32 v252, v69, v252
	v_exp_f32_e32 v71, v71
	v_add_f32_e32 v252, v70, v252
	v_cvt_pk_bf16_f32 v244, v68, v69
	v_exp_f32_e32 v72, v72
	v_mfma_f32_32x32x16_bf16 v[48:63], v[140:143], v[216:219], v[48:63]
	v_add_f32_e32 v252, v71, v252
	v_exp_f32_e32 v73, v73
	v_add_f32_e32 v252, v72, v252
	v_cvt_pk_bf16_f32 v245, v70, v71
	v_exp_f32_e32 v74, v74
	v_add_f32_e32 v252, v73, v252
	v_exp_f32_e32 v75, v75
	v_permlane32_swap_b32_e32 v242, v244
	s_waitcnt lgkmcnt(0)
	v_mfma_f32_32x32x16_bf16 v[48:63], v[144:147], v[220:223], v[48:63]
	v_permlane32_swap_b32_e32 v243, v245
	v_add_f32_e32 v252, v74, v252
	v_cvt_pk_bf16_f32 v246, v72, v73
	v_exp_f32_e32 v76, v76
	v_add_f32_e32 v252, v75, v252
	v_exp_f32_e32 v77, v77
	v_add_f32_e32 v252, v76, v252
	v_cvt_pk_bf16_f32 v247, v74, v75
	v_exp_f32_e32 v78, v78
	v_mfma_f32_32x32x16_bf16 v[48:63], v[148:151], v[224:227], v[48:63]
	s_sub_i32 s10, 0x20800, s100
	s_sub_i32 s10, s10, s101
	s_sub_i32 s11, 0x44800, s46
	s_sub_i32 s11, s11, s23
	s_mov_b32 s100, s101
	s_mov_b32 s101, s10
	s_mov_b32 s46, s23
	s_mov_b32 s23, s11
	v_add_u32_e32 v193, s46, v175
	v_add_u32_e32 v194, s46, v182
	v_add_u32_e32 v232, s46, v186
	v_add_u32_e32 v233, s46, v187
	ds_read_b128 v[228:231], v193
	ds_read_b128 v[224:227], v193 offset:4096
	v_add_f32_e32 v252, v77, v252
	v_exp_f32_e32 v79, v79
	v_add_f32_e32 v252, v78, v252
	v_cvt_pk_bf16_f32 v248, v76, v77
	v_add_f32_e32 v252, v79, v252
	v_cvt_pk_bf16_f32 v249, v78, v79
	v_fma_f32 v192, v192, v253, v252
	s_nop 0
	s_nop 0
	v_permlane32_swap_b32_e32 v246, v248
	v_permlane32_swap_b32_e32 v247, v249

.LBB0_107:
	s_add_u32 s40, s40, 0xc0000
	s_addc_u32 s41, s41, 0
	s_cmp_eq_u32 s22, s40
	s_cbranch_scc1 .LBB0_111
	s_branch .LBB0_91
